# attention: second-half global loads interleaved with the three cvts after the last QK MFMA
# speedup vs baseline: 1.0002x; 1.0002x over previous
; #define SBAR() __builtin_amdgcn_sched_barrier(0)
; #define SLOAD(i, k0) do { sr_[i].vs0 = St::ld8(&Vh[(long)((k0) + sr) * LDK + sc]); sr_[i].vs1 = St::ld8(&Vh[(long)((k0) + 32 + sr) * LDK + sc]); \
;     sr_[i].ks0 = St::ld8(&Kh[(long)((k0) + sr) * LDK + sc]); sr_[i].ks1 = St::ld8(&Kh[(long)((k0) + 32 + sr) * LDK + sc]); } while (0)
; #define RESC(a) do { if (__any((a) < 1.f)) { if (hi == 0) al_l[r32] = (a); asm volatile("s_waitcnt lgkmcnt(0)" ::: "memory"); \
;     for (int d = 0; d < 4; ++d) for (int r = 0; r < 16; ++r) o[d][r] *= al_l[crow(r, hi)]; } } while (0)
; __device__ __forceinline__ void partialSM(f32x16& p0, f32x16& p1, float& m_reg, float& mn, float& alpha) {
;     ...
;   float mnC = -mn * C;
;   for (int r = 0; r < 16; ++r) p0[r] = fmaf(p0[r], C, mnC); for (int r = 0; r < 16; ++r) p1[r] = fmaf(p1[r], C, mnC);
;   for (int r = 0; r < 16; ++r) p0[r] = __builtin_amdgcn_exp2f(p0[r]);
; }
; __device__ __forceinline__ void finishSM(f32x16& p0, f32x16& p1, float alpha, float& l_reg, bf16x8& pa0, bf16x8& pa1, bf16x8& pa2, bf16x8& pa3) {
;   for (int r = 0; r < 16; ++r) p1[r] = __builtin_amdgcn_exp2f(p1[r]);
;   float ps = 0; for (int r = 0; r < 16; ++r) ps += p0[r]; for (int r = 0; r < 16; ++r) ps += p1[r];
;   { auto rr = __builtin_amdgcn_permlane32_swap(__float_as_uint(ps), __float_as_uint(ps), false, false);
;     ps = __uint_as_float(rr[0]) + __uint_as_float(rr[1]); }
;   l_reg = l_reg * alpha + ps;
;     ...
;   PK4(p0, 0, pa0); PK4(p0, 8, pa1); PK4(p1, 0, pa2); PK4(p1, 8, pa3);
; template <typename TQ>
; __device__ __forceinline__ void attn_dense_body(const TQ* __restrict__ Qb, const bf16* __restrict__ Kh, const bf16* __restrict__ Vh,
;                                                 unsigned short* __restrict__ Ob, int seq, char* lds, const int wave_s) {
;     ...
;     RESC(alB); __syncthreads();
;     SBAR(); qkt(pA0, pA1, K_lds, qr, r32, hi);
;     finishSM(pB0, pB1, alB, l_reg, pa0, pa1, pa2, pa3); SBAR();
;     if (SDEPTH == 1 || j + 3 < NT) SLOAD(SE, (j + 1 + SDEPTH) * KVBLK); SBAR();
.LBB0_579:
	v_xor_b32_e32 v189, 0x18000, v189
	v_xor_b32_e32 v199, 0x18000, v199
	v_xor_b32_e32 v192, 0x18000, v192
	v_xor_b32_e32 v191, 0x18000, v191
	v_mul_f32_e32 v207, 0xbe0293ee, v206
	v_fmamk_f32 v80, v80, 0x3e0293ee, v207
	v_fmamk_f32 v81, v81, 0x3e0293ee, v207
	v_fmamk_f32 v82, v82, 0x3e0293ee, v207
	v_fmamk_f32 v83, v83, 0x3e0293ee, v207
	v_fmamk_f32 v84, v84, 0x3e0293ee, v207
	v_fmamk_f32 v85, v85, 0x3e0293ee, v207
	v_fmamk_f32 v86, v86, 0x3e0293ee, v207
	v_fmamk_f32 v87, v87, 0x3e0293ee, v207
	v_fmamk_f32 v88, v88, 0x3e0293ee, v207
	v_fmamk_f32 v89, v89, 0x3e0293ee, v207
	v_fmamk_f32 v90, v90, 0x3e0293ee, v207
	v_fmamk_f32 v91, v91, 0x3e0293ee, v207
	v_fmamk_f32 v92, v92, 0x3e0293ee, v207
	v_fmamk_f32 v93, v93, 0x3e0293ee, v207
	v_fmamk_f32 v94, v94, 0x3e0293ee, v207
	v_fmamk_f32 v95, v95, 0x3e0293ee, v207
	v_exp_f32_e32 v160, v80
	v_exp_f32_e32 v175, v81
	v_exp_f32_e32 v161, v82
	v_exp_f32_e32 v174, v83
	v_exp_f32_e32 v162, v84
	v_exp_f32_e32 v173, v85
	v_exp_f32_e32 v163, v86
	v_exp_f32_e32 v172, v87
	v_exp_f32_e32 v164, v88
	v_exp_f32_e32 v171, v89
	v_exp_f32_e32 v165, v90
	v_exp_f32_e32 v170, v91
	v_exp_f32_e32 v166, v92
	v_exp_f32_e32 v169, v93
	v_exp_f32_e32 v167, v94
	v_exp_f32_e32 v168, v95
	v_fmamk_f32 v216, v64, 0x3e0293ee, v207
	v_fmamk_f32 v217, v65, 0x3e0293ee, v207
	v_fmamk_f32 v218, v66, 0x3e0293ee, v207
	v_fmamk_f32 v219, v67, 0x3e0293ee, v207
	v_fmamk_f32 v224, v68, 0x3e0293ee, v207
	v_fmamk_f32 v209, v69, 0x3e0293ee, v207
	v_fmamk_f32 v210, v70, 0x3e0293ee, v207
	v_fmamk_f32 v211, v71, 0x3e0293ee, v207
	v_fmamk_f32 v212, v72, 0x3e0293ee, v207
	v_fmamk_f32 v213, v73, 0x3e0293ee, v207
	v_fmamk_f32 v214, v74, 0x3e0293ee, v207
	v_fmamk_f32 v215, v75, 0x3e0293ee, v207
	v_fmamk_f32 v208, v76, 0x3e0293ee, v207
	v_fmamk_f32 v225, v77, 0x3e0293ee, v207
	v_fmamk_f32 v226, v78, 0x3e0293ee, v207
	v_fmac_f32_e32 v207, 0x3e0293ee, v79
	s_waitcnt lgkmcnt(0)
	s_barrier
	ds_read_b128 v[64:67], v189 offset:32768
	ds_read_b128 v[68:71], v189 offset:40960
	ds_read_b128 v[228:231], v199 offset:32768
	ds_read_b128 v[232:235], v199 offset:40960
	ds_read_b128 v[240:243], v192 offset:32768
	ds_read_b128 v[244:247], v192 offset:40960
	v_exp_f32_e32 v221, v207
	s_waitcnt lgkmcnt(5)
	v_mfma_f32_32x32x16_bf16 v[80:95], v[64:67], v[112:115], 0
	v_add_f32_e32 v207, v175, v160
	v_add_f32_e32 v207, v161, v207
	v_add_f32_e32 v207, v174, v207
	v_add_f32_e32 v207, v162, v207
	v_add_f32_e32 v207, v173, v207
	v_add_f32_e32 v207, v163, v207
	v_add_f32_e32 v207, v172, v207
	s_waitcnt lgkmcnt(4)
	v_mfma_f32_32x32x16_bf16 v[64:79], v[68:71], v[112:115], 0
	v_add_f32_e32 v207, v164, v207
	v_add_f32_e32 v207, v171, v207
	v_add_f32_e32 v207, v165, v207
	v_add_f32_e32 v207, v170, v207
	v_exp_f32_e32 v194, v216
	v_add_f32_e32 v207, v166, v207
	v_exp_f32_e32 v195, v217
	s_waitcnt lgkmcnt(3)
	v_mfma_f32_32x32x16_bf16 v[80:95], v[228:231], v[108:111], v[80:95]
	v_add_f32_e32 v207, v169, v207
	v_exp_f32_e32 v196, v218
	v_add_f32_e32 v207, v167, v207
	v_exp_f32_e32 v197, v219
	v_add_f32_e32 v207, v168, v207
	v_exp_f32_e32 v216, v224
	v_add_f32_e32 v207, v194, v207
	s_waitcnt lgkmcnt(2)
	v_mfma_f32_32x32x16_bf16 v[64:79], v[232:235], v[108:111], v[64:79]
	ds_read_b128 v[228:231], v191 offset:32768
	ds_read_b128 v[232:235], v191 offset:40960
	v_exp_f32_e32 v209, v209
	v_add_f32_e32 v207, v195, v207
	v_exp_f32_e32 v210, v210
	v_add_f32_e32 v207, v196, v207
	v_exp_f32_e32 v211, v211
	v_add_f32_e32 v207, v197, v207
	s_waitcnt lgkmcnt(3)
	v_mfma_f32_32x32x16_bf16 v[80:95], v[240:243], v[120:123], v[80:95]
	v_exp_f32_e32 v212, v212
	v_add_f32_e32 v207, v216, v207
	v_exp_f32_e32 v213, v213
	v_add_f32_e32 v207, v209, v207
	v_exp_f32_e32 v214, v214
	v_add_f32_e32 v207, v210, v207
	v_exp_f32_e32 v215, v215
	s_waitcnt lgkmcnt(2)
	v_mfma_f32_32x32x16_bf16 v[64:79], v[244:247], v[120:123], v[64:79]
	ds_read_b128 v[240:243], v189 offset:32896
	ds_read_b128 v[244:247], v189 offset:41088
	v_add_f32_e32 v207, v211, v207
	v_exp_f32_e32 v217, v208
	v_add_f32_e32 v207, v212, v207
	v_exp_f32_e32 v218, v225
	v_add_f32_e32 v207, v213, v207
	v_exp_f32_e32 v219, v226
	s_waitcnt lgkmcnt(3)
	v_mfma_f32_32x32x16_bf16 v[80:95], v[228:231], v[124:127], v[80:95]
	v_add_f32_e32 v207, v214, v207
	v_add_f32_e32 v207, v215, v207
	v_add_f32_e32 v207, v217, v207
	v_add_f32_e32 v207, v218, v207
	v_add_f32_e32 v207, v219, v207
	v_add_f32_e32 v207, v221, v207
	s_waitcnt lgkmcnt(2)
	v_mfma_f32_32x32x16_bf16 v[64:79], v[232:235], v[124:127], v[64:79]
	ds_read_b128 v[228:231], v199 offset:32896
	ds_read_b128 v[232:235], v199 offset:41088
	s_waitcnt lgkmcnt(3)
	v_mfma_f32_32x32x16_bf16 v[80:95], v[240:243], v[116:119], v[80:95]
	s_waitcnt lgkmcnt(2)
	v_mfma_f32_32x32x16_bf16 v[64:79], v[244:247], v[116:119], v[64:79]
	ds_read_b128 v[240:243], v192 offset:32896
	ds_read_b128 v[244:247], v192 offset:41088
	s_waitcnt lgkmcnt(3)
	v_mfma_f32_32x32x16_bf16 v[80:95], v[228:231], v[104:107], v[80:95]
	s_waitcnt lgkmcnt(2)
	v_mfma_f32_32x32x16_bf16 v[64:79], v[232:235], v[104:107], v[64:79]
	ds_read_b128 v[228:231], v191 offset:32896
	ds_read_b128 v[232:235], v191 offset:41088
	s_waitcnt lgkmcnt(3)
	v_mfma_f32_32x32x16_bf16 v[80:95], v[240:243], v[100:103], v[80:95]
	s_waitcnt lgkmcnt(2)
	v_mfma_f32_32x32x16_bf16 v[64:79], v[244:247], v[100:103], v[64:79]
	v_cvt_pk_bf16_f32 v160, v160, v175
	v_cvt_pk_bf16_f32 v161, v161, v174
	v_cvt_pk_bf16_f32 v162, v162, v173
	v_cvt_pk_bf16_f32 v163, v163, v172
	v_cvt_pk_bf16_f32 v164, v164, v171
	v_cvt_pk_bf16_f32 v165, v165, v170
	s_waitcnt lgkmcnt(1)
	v_mfma_f32_32x32x16_bf16 v[80:95], v[228:231], v[96:99], v[80:95]
	v_cvt_pk_bf16_f32 v166, v166, v169
	v_cvt_pk_bf16_f32 v167, v167, v168
	v_cvt_pk_bf16_f32 v168, v194, v195
	v_cvt_pk_bf16_f32 v169, v196, v197
	v_cvt_pk_bf16_f32 v170, v216, v209
	v_cvt_pk_bf16_f32 v171, v210, v211
	v_cvt_pk_bf16_f32 v172, v212, v213
	s_waitcnt lgkmcnt(0)
	v_mfma_f32_32x32x16_bf16 v[64:79], v[232:235], v[96:99], v[64:79]
	s_add_i32 s50, s50, 2
	s_cmp_ge_u32 s50, s49
	s_cselect_b64 s[44:45], -1, 0
	s_and_b64 vcc, exec, s[44:45]
	s_cbranch_vccnz .Lattn_skip_loads
	v_cvt_pk_bf16_f32 v173, v214, v215
	global_load_dwordx4 v[128:131], v176, s[52:53]
	v_cvt_pk_bf16_f32 v174, v217, v218
	global_load_dwordx4 v[132:135], v176, s[52:53] offset:-512
	s_add_u32 s40, s52, 0x18000
	s_addc_u32 s41, s53, 0
	v_cvt_pk_bf16_f32 v175, v219, v221
	global_load_dwordx4 v[136:139], v176, s[40:41]
	s_add_u32 s52, s52, 0x30000
	s_addc_u32 s53, s53, 0
	global_load_dwordx4 v[140:143], v176, s[40:41] offset:-512

; #define SBAR() __builtin_amdgcn_sched_barrier(0)
; #define SLOAD(i, k0) do { sr_[i].vs0 = St::ld8(&Vh[(long)((k0) + sr) * LDK + sc]); sr_[i].vs1 = St::ld8(&Vh[(long)((k0) + 32 + sr) * LDK + sc]); \
;     sr_[i].ks0 = St::ld8(&Kh[(long)((k0) + sr) * LDK + sc]); sr_[i].ks1 = St::ld8(&Kh[(long)((k0) + 32 + sr) * LDK + sc]); } while (0)
; template <typename TQ>
; __device__ __forceinline__ void attn_dense_body(const TQ* __restrict__ Qb, const bf16* __restrict__ Kh, const bf16* __restrict__ Vh,
;                                                 unsigned short* __restrict__ Ob, int seq, char* lds, const int wave_s) {
;     ...
;     finishSM(pB0, pB1, alB, l_reg, pa0, pa1, pa2, pa3); SBAR();
;     if (SDEPTH == 1 || j + 3 < NT) SLOAD(SE, (j + 1 + SDEPTH) * KVBLK); SBAR();
.Lattn_skip_loads:
	s_waitcnt vmcnt(0)
	v_cvt_pk_bf16_f32 v173, v214, v215
	v_cvt_pk_bf16_f32 v174, v217, v218
	v_cvt_pk_bf16_f32 v175, v219, v221
	s_branch .LBB0_581
